# v29 + attention tile loop: hipcc's wave-uniform ballot (v_cndmask/v_cmp/s_cmp vcc) trimmed to s_cmp_lg_u64 on the v_cmp mask at 4 sites
# speedup vs baseline: 1.0015x; 1.0013x over previous
.Lattn_g15_u1:
	s_waitcnt lgkmcnt(0)
	s_barrier
	v_add3_u32 v208, s32, v179, v177
	s_waitcnt vmcnt(3)
	ds_write_b128 v208, v[100:103]
	v_add3_u32 v208, s32, v180, v177
	s_waitcnt vmcnt(2)
	ds_write_b128 v208, v[96:99]
	v_add3_u32 v208, s94, v176, v178
	s_waitcnt vmcnt(1)
	ds_write_b128 v208, v[104:107] offset:34816
	s_waitcnt vmcnt(0)
	ds_write_b128 v208, v[108:111] offset:44032
	v_lshl_add_u64 v[66:67], v[152:153], 0, s[98:99]
	v_lshl_add_u64 v[64:65], v[152:153], 0, s[100:101]
	global_load_dwordx4 v[100:103], v[66:67], off
	global_load_dwordx4 v[96:99], v[64:65], off
	v_lshl_add_u64 v[66:67], v[150:151], 0, s[44:45]
	s_lshr_b32 s0, s84, 2
	v_lshl_add_u64 v[64:65], v[150:151], 0, s[46:47]
	s_cmp_eq_u32 s0, s81
	global_load_dwordx4 v[104:107], v[66:67], off offset:128
	global_load_dwordx4 v[108:111], v[64:65], off offset:128
	s_cselect_b64 s[8:9], -1, 0
	s_lshl_b32 s1, 1, s0
	v_and_b32_e32 v64, s1, v173
	s_cmp_lg_u32 s0, s81
	v_cmp_ne_u32_e64 s[0:1], 0, v64
	s_mov_b64 s[4:5], -1
	s_cbranch_scc0 .LBB0_1732
	s_cmp_lg_u64 s[0:1], 0
	s_cselect_b64 s[10:11], -1, 0
	s_and_b32 s17, s84, 3
	s_cbranch_execz .LBB0_1733

.LBB0_1740:
	s_and_b32 s0, s14, 1
	s_mul_i32 s1, s0, 0x4400
	s_add_i32 s16, s1, 0
	s_waitcnt vmcnt(0)
	s_lshl_b32 s0, s0, 10
	s_add_i32 s15, s16, s0
	s_lshr_b32 s0, s14, 2
	s_cmp_eq_u32 s0, s81
	v_lshrrev_b32_e32 v64, s0, v173
	s_cselect_b64 s[8:9], -1, 0
	v_and_b32_e32 v64, 1, v64
	v_cmp_eq_u32_e64 s[0:1], 1, v64
	s_mov_b64 s[4:5], -1
	s_and_b64 vcc, exec, s[8:9]
	s_waitcnt lgkmcnt(0)
	s_barrier
	s_cbranch_vccnz .LBB0_1743
	s_cmp_lg_u64 s[0:1], 0
	s_cselect_b64 s[10:11], -1, 0
	s_and_b32 s14, s14, 3
	s_cbranch_execz .LBB0_1744

.Lattn_g15_u2:
	s_waitcnt lgkmcnt(0)
	s_barrier
	v_add3_u32 v208, s32, v179, v177
	s_waitcnt vmcnt(3)
	ds_write_b128 v208, v[100:103]
	v_add3_u32 v208, s32, v180, v177
	s_waitcnt vmcnt(2)
	ds_write_b128 v208, v[96:99]
	v_add3_u32 v208, s94, v176, v178
	s_waitcnt vmcnt(1)
	ds_write_b128 v208, v[104:107] offset:34816
	s_waitcnt vmcnt(0)
	ds_write_b128 v208, v[108:111] offset:44032
	v_lshl_add_u64 v[66:67], v[152:153], 0, s[98:99]
	v_lshl_add_u64 v[64:65], v[152:153], 0, s[100:101]
	global_load_dwordx4 v[100:103], v[66:67], off
	global_load_dwordx4 v[96:99], v[64:65], off
	v_lshl_add_u64 v[66:67], v[150:151], 0, s[44:45]
	s_lshr_b32 s0, s15, 2
	v_lshl_add_u64 v[64:65], v[150:151], 0, s[46:47]
	s_cmp_eq_u32 s0, s80
	global_load_dwordx4 v[104:107], v[66:67], off offset:128
	global_load_dwordx4 v[108:111], v[64:65], off offset:128
	s_cselect_b64 s[8:9], -1, 0
	s_lshl_b32 s1, 1, s0
	v_and_b32_e32 v64, s1, v172
	s_cmp_lg_u32 s0, s80
	v_cmp_ne_u32_e64 s[0:1], 0, v64
	s_mov_b64 s[4:5], -1
	s_cbranch_scc0 .LBB0_1775
	s_cmp_lg_u64 s[0:1], 0
	s_cselect_b64 s[10:11], -1, 0
	s_and_b32 s18, s15, 3
	s_cbranch_execz .LBB0_1776

.LBB0_1783:
	s_and_b32 s0, s14, 1
	s_mul_i32 s1, s0, 0x4400
	s_add_i32 s15, s1, 0
	s_waitcnt vmcnt(0)
	s_lshl_b32 s0, s0, 10
	s_add_i32 s12, s15, s0
	s_lshr_b32 s0, s14, 2
	s_cmp_eq_u32 s0, s80
	v_lshrrev_b32_e32 v64, s0, v172
	s_cselect_b64 s[8:9], -1, 0
	v_and_b32_e32 v64, 1, v64
	v_cmp_eq_u32_e64 s[0:1], 1, v64
	s_mov_b64 s[4:5], -1
	s_and_b64 vcc, exec, s[8:9]
	s_waitcnt lgkmcnt(0)
	s_barrier
	s_cbranch_vccnz .LBB0_1786
	s_cmp_lg_u64 s[0:1], 0
	s_cselect_b64 s[10:11], -1, 0
	s_and_b32 s13, s14, 3
	s_cbranch_execz .LBB0_1787
